# barrier 3 (QKV0 to ATT0) also replaced by per-row-block qkv-done counters (ctx block + the 8 blocks of the batch)
# baseline (speedup 1.0000x reference)
.LBB0_274:
	s_waitcnt vmcnt(0)
	s_waitcnt vmcnt(0) lgkmcnt(0)
	s_barrier
	s_mov_b64 s[4:5], exec
	v_readlane_b32 s0, v219, 25
	v_readlane_b32 s1, v219, 26
	s_and_b64 s[0:1], s[4:5], s[0:1]
	s_mov_b64 exec, s[0:1]
	s_cbranch_execz .LBB0_326
	v_readlane_b32 s0, v219, 27
	v_readlane_b32 s1, v219, 28
	v_readlane_b32 s2, v219, 30
	s_waitcnt vmcnt(0) lgkmcnt(0)
	buffer_inv sc1
	s_and_b32 s3, s2, 31
	s_lshl_b32 s3, s3, 7
	s_add_i32 s3, s3, 0x70
	v_mov_b32_e32 v0, 1
	v_mov_b32_e32 v1, s3
	s_nop 1
	global_atomic_add v1, v0, s[0:1]
	s_lshr_b32 s3, s2, 4
	s_lshl_b32 s3, s3, 7
	s_add_i32 s3, s3, 0x70
	s_mov_b32 s10, 1

.Lqb3_cn:
	s_add_i32 s3, s3, 0x80
	s_sub_i32 s10, s10, 1
	s_cmp_lg_u32 s10, 0
	s_cbranch_scc1 .Lqb3_cw
	s_bfe_u32 s11, s2, 0x10002
	s_lshl_b32 s11, s11, 3
	s_add_i32 s11, s11, 16
	s_lshl_b32 s3, s11, 7
	s_add_i32 s3, s3, 0x70
	s_mov_b32 s10, 8

.Lqb3_ln:
	s_add_i32 s3, s3, 0x80
	s_sub_i32 s10, s10, 1
	s_cmp_lg_u32 s10, 0
	s_cbranch_scc1 .Lqb3_lw
	s_waitcnt vmcnt(0)
.LBB0_326:
	s_or_b64 exec, exec, s[4:5]
	v_readlane_b32 s0, v219, 9
	v_lshlrev_b32_e32 v20, 2, v149
	v_readlane_b32 s8, v219, 17
	v_readlane_b32 s9, v219, 18
	s_waitcnt lgkmcnt(0)
	s_barrier
	s_nop 2
	global_load_dword v0, v20, s[8:9]
	global_load_dword v1, v20, s[8:9] offset:256
	global_load_dword v2, v20, s[8:9] offset:512
	global_load_dword v3, v20, s[8:9] offset:768
	v_mbcnt_hi_u32_b32 v4, -1, v163
	v_and_b32_e32 v5, 64, v4
	v_xor_b32_e32 v6, 32, v4
	v_add_u32_e32 v5, 64, v5
	v_cmp_lt_i32_e32 vcc, v6, v5
	v_xor_b32_e32 v7, 16, v4
	v_xor_b32_e32 v8, 8, v4
	v_cndmask_b32_e32 v6, v4, v6, vcc
	v_lshlrev_b32_e32 v172, 2, v6
	v_cmp_lt_i32_e32 vcc, v7, v5
	v_xor_b32_e32 v9, 4, v4
	v_xor_b32_e32 v10, 2, v4
	v_cndmask_b32_e32 v7, v4, v7, vcc
	v_lshlrev_b32_e32 v173, 2, v7
	v_cmp_lt_i32_e32 vcc, v8, v5
	v_xor_b32_e32 v11, 1, v4
	s_bcnt1_i32_b32 s0, s78
	s_bitcmp0_b32 s0, 0
	s_cselect_b64 s[8:9], -1, 0
	v_readlane_b32 s1, v219, 10
	v_readlane_b32 s2, v219, 11
	v_readlane_b32 s3, v219, 12
	v_readlane_b32 s4, v219, 13
	v_readlane_b32 s5, v219, 14
	v_readlane_b32 s6, v219, 15
	v_readlane_b32 s7, v219, 16
	v_readlane_b32 s10, v219, 19
	v_readlane_b32 s11, v219, 20
	v_readlane_b32 s12, v219, 21
	v_readlane_b32 s13, v219, 22
	v_readlane_b32 s14, v219, 23
	v_readlane_b32 s15, v219, 24
	s_waitcnt vmcnt(2)
	v_mul_f32_e32 v6, v0, v1
	ds_bpermute_b32 v6, v172, v6
	s_waitcnt vmcnt(0)
	v_mul_f32_e32 v12, v2, v3
	ds_bpermute_b32 v12, v172, v12
	s_waitcnt lgkmcnt(1)
	v_fmac_f32_e32 v6, v0, v1
	ds_bpermute_b32 v0, v173, v6
	s_waitcnt lgkmcnt(1)
	v_fmac_f32_e32 v12, v2, v3
	ds_bpermute_b32 v1, v173, v12
	v_cndmask_b32_e32 v2, v4, v8, vcc
	v_lshlrev_b32_e32 v174, 2, v2
	s_waitcnt lgkmcnt(1)
	v_add_f32_e32 v0, v6, v0
	ds_bpermute_b32 v2, v174, v0
	s_waitcnt lgkmcnt(1)
	v_add_f32_e32 v1, v12, v1
	ds_bpermute_b32 v3, v174, v1
	v_cmp_lt_i32_e32 vcc, v9, v5
	s_waitcnt lgkmcnt(1)
	v_add_f32_e32 v0, v0, v2
	v_cndmask_b32_e32 v6, v4, v9, vcc
	v_lshlrev_b32_e32 v175, 2, v6
	s_waitcnt lgkmcnt(0)
	v_add_f32_e32 v1, v1, v3
	ds_bpermute_b32 v2, v175, v0
	ds_bpermute_b32 v3, v175, v1
	v_cmp_lt_i32_e32 vcc, v10, v5
	s_waitcnt lgkmcnt(1)
	v_add_f32_e32 v0, v0, v2
	v_cndmask_b32_e32 v6, v4, v10, vcc
	v_lshlrev_b32_e32 v176, 2, v6
	s_waitcnt lgkmcnt(0)
	v_add_f32_e32 v1, v1, v3
	ds_bpermute_b32 v2, v176, v0
	ds_bpermute_b32 v3, v176, v1
	v_cmp_lt_i32_e32 vcc, v11, v5
	s_waitcnt lgkmcnt(1)
	v_add_f32_e32 v21, v0, v2
	v_cndmask_b32_e32 v4, v4, v11, vcc
	v_lshlrev_b32_e32 v177, 2, v4
	s_waitcnt lgkmcnt(0)
	v_add_f32_e32 v22, v1, v3
	ds_bpermute_b32 v23, v177, v21
	ds_bpermute_b32 v24, v177, v22
	s_and_b64 vcc, exec, s[8:9]
	s_cbranch_vccnz .LBB0_347
	s_add_i32 s0, s78, 0xc0
	s_cmpk_gt_i32 s0, 0x25f
	s_waitcnt lgkmcnt(0)
	s_barrier
	s_cbranch_scc1 .LBB0_346
	s_movk_i32 s1, 0x2100
	v_lshrrev_b32_e32 v25, 3, v149
	v_and_b32_e32 v4, 56, v144
	s_cmpk_eq_i32 s58, 0x100
	v_mad_u32_u24 v1, v148, s1, 0
	v_lshrrev_b32_e32 v0, 5, v149
	v_and_b32_e32 v2, 31, v168
	v_mul_u32_u24_e32 v3, 0x84, v4
	v_lshlrev_b32_e32 v7, 2, v25
	s_cselect_b64 s[6:7], -1, 0
	v_mov_b32_e32 v5, 0
	v_lshl_add_u32 v6, v2, 2, v1
	s_movk_i32 s1, 0x84
	v_add3_u32 v26, v1, v3, v7
	v_or_b32_e32 v27, 8, v25
	v_or_b32_e32 v28, 16, v25
	v_or_b32_e32 v29, 24, v25
	v_mov_b32_e32 v1, v0
	s_movk_i32 s2, 0x187f
	s_movk_i32 s3, 0x1ff
	s_movk_i32 s10, 0xcff
	v_lshlrev_b32_e32 v8, 2, v2
	v_lshlrev_b32_e32 v10, 1, v4
	v_mov_b32_e32 v30, 0xffffe780
	v_mov_b32_e32 v31, 0xc00
	v_mov_b32_e32 v32, 0x600
	v_mov_b32_e32 v33, 0x2c0000
	v_mov_b32_e32 v34, 0x1400000
	v_mov_b32_e32 v35, 0x2980000
	v_mov_b32_e32 v36, 0x900000
	v_mov_b32_e32 v37, 0x1e80000
	v_mov_b32_e32 v38, 0x700000
	v_mov_b32_e32 v39, 0x1c80000
	v_mov_b32_e32 v40, 0x100000
	v_mov_b32_e32 v41, 0x1980000
	s_branch .LBB0_330

.LBB0_396:
	s_waitcnt vmcnt(0)
	s_waitcnt lgkmcnt(0)
	s_barrier
	s_mov_b64 s[4:5], exec
	v_readlane_b32 s0, v219, 25
	v_readlane_b32 s1, v219, 26
	s_and_b64 s[0:1], s[4:5], s[0:1]
	s_mov_b64 exec, s[0:1]
	s_cbranch_execz .LBB0_448
	v_readlane_b32 s0, v219, 27
	v_readlane_b32 s1, v219, 28
	v_readlane_b32 s2, v219, 29
	v_mov_b32_e32 v0, 0x24000
	s_waitcnt vmcnt(0) lgkmcnt(0)
	buffer_inv sc1
	ds_read_b32 v2, v0
	ds_read_b32 v0, v0 offset:4
	s_lshl_b32 s3, s2, 8
	s_add_i32 s14, s3, 0x2400
	s_add_i32 s3, s3, 0x1400
	v_mov_b32_e32 v1, s3
	s_waitcnt lgkmcnt(0)
	v_readfirstlane_b32 s10, v2
	v_readfirstlane_b32 s11, v0
	v_mov_b32_e32 v0, 1
	s_nop 1
	global_atomic_add v2, v1, v0, s[0:1] sc0
	s_mul_i32 s10, s10, 2
	s_mul_i32 s11, s11, 2
	s_waitcnt vmcnt(0)
	v_readfirstlane_b32 s13, v2
	s_nop 1
	s_add_i32 s13, s13, 1
	s_cmp_lg_u32 s13, s10
	s_cbranch_scc1 .Lnb4_wait
	v_mov_b32_e32 v1, 0x3400
	global_atomic_add v2, v1, v0, s[0:1] sc0
	s_waitcnt vmcnt(0)
	v_readfirstlane_b32 s13, v2
	s_nop 1
	s_add_i32 s13, s13, 1
	s_cmp_lg_u32 s13, s11
	s_cbranch_scc1 .Lnb4_wait
	v_mov_b32_e32 v1, 0x2400
	global_atomic_add v1, v0, s[0:1]
	global_atomic_add v1, v0, s[0:1] offset:256
	global_atomic_add v1, v0, s[0:1] offset:512
	global_atomic_add v1, v0, s[0:1] offset:768
	global_atomic_add v1, v0, s[0:1] offset:1024
	global_atomic_add v1, v0, s[0:1] offset:1280
	global_atomic_add v1, v0, s[0:1] offset:1536
	global_atomic_add v1, v0, s[0:1] offset:1792
	global_atomic_add v1, v0, s[0:1] offset:2048
	global_atomic_add v1, v0, s[0:1] offset:2304
	global_atomic_add v1, v0, s[0:1] offset:2560
	global_atomic_add v1, v0, s[0:1] offset:2816
	global_atomic_add v1, v0, s[0:1] offset:3072
	global_atomic_add v1, v0, s[0:1] offset:3328
	global_atomic_add v1, v0, s[0:1] offset:3584
	global_atomic_add v1, v0, s[0:1] offset:3840

.Lgu0h_skip:
	s_waitcnt vmcnt(0)
	s_waitcnt vmcnt(0) lgkmcnt(0)
	s_barrier
	s_mov_b64 s[4:5], exec
	v_readlane_b32 s0, v219, 25
	v_readlane_b32 s1, v219, 26
	s_and_b64 s[0:1], s[4:5], s[0:1]
	s_mov_b64 exec, s[0:1]
	s_cbranch_execz .LBB0_745
	v_readlane_b32 s0, v219, 27
	v_readlane_b32 s1, v219, 28
	v_readlane_b32 s2, v219, 29
	v_mov_b32_e32 v0, 0x24000
	s_waitcnt vmcnt(0) lgkmcnt(0)
	buffer_inv sc1
	ds_read_b32 v2, v0
	ds_read_b32 v0, v0 offset:4
	s_lshl_b32 s3, s2, 8
	s_add_i32 s14, s3, 0x2400
	s_add_i32 s3, s3, 0x1400
	v_mov_b32_e32 v1, s3
	s_waitcnt lgkmcnt(0)
	v_readfirstlane_b32 s10, v2
	v_readfirstlane_b32 s11, v0
	v_mov_b32_e32 v0, 1
	s_nop 1
	global_atomic_add v2, v1, v0, s[0:1] sc0
	s_mul_i32 s10, s10, 3
	s_mul_i32 s11, s11, 3
	s_waitcnt vmcnt(0)
	v_readfirstlane_b32 s13, v2
	s_nop 1
	s_add_i32 s13, s13, 1
	s_cmp_lg_u32 s13, s10
	s_cbranch_scc1 .Lnb7_wait
	v_mov_b32_e32 v1, 0x3400
	global_atomic_add v2, v1, v0, s[0:1] sc0
	s_waitcnt vmcnt(0)
	v_readfirstlane_b32 s13, v2
	s_nop 1
	s_add_i32 s13, s13, 1
	s_cmp_lg_u32 s13, s11
	s_cbranch_scc1 .Lnb7_wait
	v_mov_b32_e32 v1, 0x2400
	global_atomic_add v1, v0, s[0:1]
	global_atomic_add v1, v0, s[0:1] offset:256
	global_atomic_add v1, v0, s[0:1] offset:512
	global_atomic_add v1, v0, s[0:1] offset:768
	global_atomic_add v1, v0, s[0:1] offset:1024
	global_atomic_add v1, v0, s[0:1] offset:1280
	global_atomic_add v1, v0, s[0:1] offset:1536
	global_atomic_add v1, v0, s[0:1] offset:1792
	global_atomic_add v1, v0, s[0:1] offset:2048
	global_atomic_add v1, v0, s[0:1] offset:2304
	global_atomic_add v1, v0, s[0:1] offset:2560
	global_atomic_add v1, v0, s[0:1] offset:2816
	global_atomic_add v1, v0, s[0:1] offset:3072
	global_atomic_add v1, v0, s[0:1] offset:3328
	global_atomic_add v1, v0, s[0:1] offset:3584
	global_atomic_add v1, v0, s[0:1] offset:3840

.Lqb10_cw:
	v_mov_b32_e32 v1, s3
	s_mov_b32 s15, 0
.Lqb10_cs:
	global_load_dword v2, v1, s[0:1] sc1
	s_waitcnt vmcnt(0)
	v_readfirstlane_b32 s13, v2
	s_nop 1
	s_cmp_ge_u32 s13, 16
	s_cbranch_scc1 .Lqb10_cn
	s_sleep 1
	s_add_i32 s15, s15, 1
	s_cmp_lt_u32 s15, 0x200000
	s_cbranch_scc1 .Lqb10_cs
.Lqb10_cn:
	s_add_i32 s3, s3, 0x80
	s_sub_i32 s10, s10, 1
	s_cmp_lg_u32 s10, 0
	s_cbranch_scc1 .Lqb10_cw
	s_bfe_u32 s11, s2, 0x10002
	s_lshl_b32 s11, s11, 3
	s_add_i32 s11, s11, 16
	s_bfe_u32 s14, s2, 0x30004
	s_sub_i32 s13, s14, 1
	s_max_i32 s13, s13, 0
	s_add_i32 s14, s14, 1
	s_min_i32 s14, s14, 7
	s_sub_i32 s10, s14, s13
	s_add_i32 s10, s10, 1
	s_add_i32 s3, s11, s13
	s_lshl_b32 s3, s3, 7
	s_add_i32 s3, s3, 0x70
.Lqb10_lw:
	v_mov_b32_e32 v1, s3
	s_mov_b32 s15, 0
.Lqb10_ls:
	global_load_dword v2, v1, s[0:1] sc1
	s_waitcnt vmcnt(0)
	v_readfirstlane_b32 s13, v2
	s_nop 1
	s_cmp_ge_u32 s13, 16
	s_cbranch_scc1 .Lqb10_ln
	s_sleep 1
	s_add_i32 s15, s15, 1
	s_cmp_lt_u32 s15, 0x200000
	s_cbranch_scc1 .Lqb10_ls
.Lqb10_ln:
	s_add_i32 s3, s3, 0x80
	s_sub_i32 s10, s10, 1
	s_cmp_lg_u32 s10, 0
	s_cbranch_scc1 .Lqb10_lw
	s_waitcnt vmcnt(0)
